# attention PV with swapped MFMA operands (O^T: q along lanes): rescale and 1/l become per-lane scalars (no LDS round trip), epilogue stores 16 B per lane via permlane32 swap instead of 2 B; K tile swiz
# baseline (speedup 1.0000x reference)
.Lam_go:
	s_bfe_u32 s14, s46, 0x10001
	s_lshl_b32 s15, s12, 9
	s_lshl_b32 s28, s14, 8
	s_add_i32 s28, s28, s15
	s_lshl_b32 s8, s10, 12
	s_add_i32 s8, s8, s28
	s_add_u32 s16, s40, s8
	s_addc_u32 s17, s41, 0
	s_lshl_b32 s8, s11, 12
	s_add_i32 s9, s8, s28
	s_add_u32 s18, s42, s9
	s_addc_u32 s19, s43, 0
	s_add_i32 s9, s8, s15
	s_add_u32 s20, s44, s9
	s_addc_u32 s21, s45, 0
	s_lshl_b32 s8, s10, 13
	s_lshl_b32 s9, s28, 1
	s_add_i32 s8, s8, s9
	s_add_u32 s22, s48, s8
	s_addc_u32 s23, s49, 0
	v_mbcnt_lo_u32_b32 v96, -1, 0
	v_mbcnt_hi_u32_b32 v96, -1, v96
	s_lshr_b32 s36, s84, 6
	s_lshl_b32 s38, s36, 3
	s_lshl_b32 s39, s36, 11
	s_lshl_b32 s47, s36, 12
	s_add_i32 s47, s47, 0x4000
	s_lshl_b32 s50, s36, 8
	s_add_i32 s50, s50, 0x18000
	v_and_b32_e32 v240, 31, v96
	v_lshrrev_b32_e32 v241, 5, v96
	s_lshl_b32 s37, s36, 5
	v_add_u32_e32 v242, s37, v240
	v_lshlrev_b32_e32 v242, 12, v242
	v_lshl_add_u32 v242, v241, 4, v242
	global_load_dwordx4 v[130:133], v242, s[16:17]
	global_load_dwordx4 v[134:137], v242, s[16:17] offset:32
	global_load_dwordx4 v[138:141], v242, s[16:17] offset:64
	global_load_dwordx4 v[142:145], v242, s[16:17] offset:96
	global_load_dwordx4 v[146:149], v242, s[16:17] offset:128
	global_load_dwordx4 v[150:153], v242, s[16:17] offset:160
	global_load_dwordx4 v[154:157], v242, s[16:17] offset:192
	global_load_dwordx4 v[158:161], v242, s[16:17] offset:224
	v_lshlrev_b32_e32 v243, 8, v240
	v_and_b32_e32 v238, 15, v240
	v_lshlrev_b32_e32 v238, 4, v238
	v_lshlrev_b32_e32 v239, 4, v241
	v_mov_b32_e32 v228, v239
	v_xor_b32_e32 v228, v228, v238
	v_add_u32_e32 v228, v228, v243
	v_or_b32_e32 v229, 32, v239
	v_xor_b32_e32 v229, v229, v238
	v_add_u32_e32 v229, v229, v243
	v_or_b32_e32 v230, 64, v239
	v_xor_b32_e32 v230, v230, v238
	v_add_u32_e32 v230, v230, v243
	v_or_b32_e32 v231, 96, v239
	v_xor_b32_e32 v231, v231, v238
	v_add_u32_e32 v231, v231, v243
	v_or_b32_e32 v232, 128, v239
	v_xor_b32_e32 v232, v232, v238
	v_add_u32_e32 v232, v232, v243
	v_or_b32_e32 v233, 160, v239
	v_xor_b32_e32 v233, v233, v238
	v_add_u32_e32 v233, v233, v243
	v_or_b32_e32 v234, 192, v239
	v_xor_b32_e32 v234, v234, v238
	v_add_u32_e32 v234, v234, v243
	v_or_b32_e32 v235, 224, v239
	v_xor_b32_e32 v235, v235, v238
	v_add_u32_e32 v235, v235, v243
	v_and_b32_e32 v238, 3, v96
	v_lshlrev_b32_e32 v236, 3, v238
	v_bfe_u32 v238, v96, 2, 2
	v_lshl_or_b32 v236, v238, 6, v236
	v_bfe_u32 v238, v96, 4, 1
	v_lshl_or_b32 v236, v238, 5, v236
	v_lshl_or_b32 v236, v241, 8, v236
	v_add_u32_e32 v237, 0x10000, v236
	v_add_u32_e32 v236, 0x4000, v236
	v_lshrrev_b32_e32 v238, 4, v96
	v_and_b32_e32 v239, 15, v96
	v_add_u32_e32 v243, 0, v238
	v_add_u32_e32 v243, s38, v243
	v_and_b32_e32 v242, 15, v243
	v_xor_b32_e32 v244, v239, v242
	v_lshlrev_b32_e32 v244, 4, v244
	v_lshl_add_u32 v244, v243, 12, v244
	v_add_u32_e32 v243, 4, v238
	v_add_u32_e32 v243, s38, v243
	v_and_b32_e32 v242, 15, v243
	v_xor_b32_e32 v245, v239, v242
	v_lshlrev_b32_e32 v245, 4, v245
	v_lshl_add_u32 v245, v243, 12, v245
	v_lshrrev_b32_e32 v238, 2, v240
	v_add_u32_e32 v238, s38, v238
	v_and_b32_e32 v239, 0xfffffff3, v238
	v_and_b32_e32 v243, 4, v238
	v_lshl_or_b32 v239, v243, 1, v239
	v_and_b32_e32 v243, 8, v238
	v_lshrrev_b32_e32 v243, 1, v243
	v_or_b32_e32 v239, v239, v243
	v_lshlrev_b32_e32 v239, 12, v239
	v_and_b32_e32 v238, 3, v240
	v_lshlrev_b32_e32 v238, 4, v238
	v_add_u32_e32 v243, 0, v241
	v_lshl_add_u32 v243, v243, 6, v238
	v_add_u32_e32 v246, v239, v243
	v_add_u32_e32 v243, 2, v241
	v_lshl_add_u32 v243, v243, 6, v238
	v_add_u32_e32 v247, v239, v243
	v_add_u32_e32 v243, 4, v241
	v_lshl_add_u32 v243, v243, 6, v238
	v_add_u32_e32 v248, v239, v243
	v_add_u32_e32 v243, 6, v241
	v_lshl_add_u32 v243, v243, 6, v238
	v_add_u32_e32 v249, v239, v243
	v_mov_b32_e32 v238, 0xf149f2ca
	v_mov_b32_e32 v239, 0
	v_mov_b32_e32 v0, 0
	v_mov_b32_e32 v1, 0
	v_mov_b32_e32 v2, 0
	v_mov_b32_e32 v3, 0
	v_mov_b32_e32 v4, 0
	v_mov_b32_e32 v5, 0
	v_mov_b32_e32 v6, 0
	v_mov_b32_e32 v7, 0
	v_mov_b32_e32 v8, 0
	v_mov_b32_e32 v9, 0
	v_mov_b32_e32 v10, 0
	v_mov_b32_e32 v11, 0
	v_mov_b32_e32 v12, 0
	v_mov_b32_e32 v13, 0
	v_mov_b32_e32 v14, 0
	v_mov_b32_e32 v15, 0
	v_mov_b32_e32 v16, 0
	v_mov_b32_e32 v17, 0
	v_mov_b32_e32 v18, 0
	v_mov_b32_e32 v19, 0
	v_mov_b32_e32 v20, 0
	v_mov_b32_e32 v21, 0
	v_mov_b32_e32 v22, 0
	v_mov_b32_e32 v23, 0
	v_mov_b32_e32 v24, 0
	v_mov_b32_e32 v25, 0
	v_mov_b32_e32 v26, 0
	v_mov_b32_e32 v27, 0
	v_mov_b32_e32 v28, 0
	v_mov_b32_e32 v29, 0
	v_mov_b32_e32 v30, 0
	v_mov_b32_e32 v31, 0
	v_mov_b32_e32 v32, 0
	v_mov_b32_e32 v33, 0
	v_mov_b32_e32 v34, 0
	v_mov_b32_e32 v35, 0
	v_mov_b32_e32 v36, 0
	v_mov_b32_e32 v37, 0
	v_mov_b32_e32 v38, 0
	v_mov_b32_e32 v39, 0
	v_mov_b32_e32 v40, 0
	v_mov_b32_e32 v41, 0
	v_mov_b32_e32 v42, 0
	v_mov_b32_e32 v43, 0
	v_mov_b32_e32 v44, 0
	v_mov_b32_e32 v45, 0
	v_mov_b32_e32 v46, 0
	v_mov_b32_e32 v47, 0
	v_mov_b32_e32 v48, 0
	v_mov_b32_e32 v49, 0
	v_mov_b32_e32 v50, 0
	v_mov_b32_e32 v51, 0
	v_mov_b32_e32 v52, 0
	v_mov_b32_e32 v53, 0
	v_mov_b32_e32 v54, 0
	v_mov_b32_e32 v55, 0
	v_mov_b32_e32 v56, 0
	v_mov_b32_e32 v57, 0
	v_mov_b32_e32 v58, 0
	v_mov_b32_e32 v59, 0
	v_mov_b32_e32 v60, 0
	v_mov_b32_e32 v61, 0
	v_mov_b32_e32 v62, 0
	v_mov_b32_e32 v63, 0
	v_mov_b32_e32 v64, 0
	v_mov_b32_e32 v65, 0
	v_mov_b32_e32 v66, 0
	v_mov_b32_e32 v67, 0
	v_mov_b32_e32 v68, 0
	v_mov_b32_e32 v69, 0
	v_mov_b32_e32 v70, 0
	v_mov_b32_e32 v71, 0
	v_mov_b32_e32 v72, 0
	v_mov_b32_e32 v73, 0
	v_mov_b32_e32 v74, 0
	v_mov_b32_e32 v75, 0
	v_mov_b32_e32 v76, 0
	v_mov_b32_e32 v77, 0
	v_mov_b32_e32 v78, 0
	v_mov_b32_e32 v79, 0
	v_mov_b32_e32 v80, 0
	v_mov_b32_e32 v81, 0
	v_mov_b32_e32 v82, 0
	v_mov_b32_e32 v83, 0
	v_mov_b32_e32 v84, 0
	v_mov_b32_e32 v85, 0
	v_mov_b32_e32 v86, 0
	v_mov_b32_e32 v87, 0
	v_mov_b32_e32 v88, 0
	v_mov_b32_e32 v89, 0
	v_mov_b32_e32 v90, 0
	v_mov_b32_e32 v91, 0
	v_mov_b32_e32 v92, 0
	v_mov_b32_e32 v93, 0
	v_mov_b32_e32 v94, 0
	v_mov_b32_e32 v95, 0
	v_mov_b32_e32 v98, 0
	v_mov_b32_e32 v99, 0
	v_mov_b32_e32 v100, 0
	v_mov_b32_e32 v101, 0
	v_mov_b32_e32 v102, 0
	v_mov_b32_e32 v103, 0
	v_mov_b32_e32 v104, 0
	v_mov_b32_e32 v105, 0
	v_mov_b32_e32 v106, 0
	v_mov_b32_e32 v107, 0
	v_mov_b32_e32 v108, 0
	v_mov_b32_e32 v109, 0
	v_mov_b32_e32 v110, 0
	v_mov_b32_e32 v111, 0
	v_mov_b32_e32 v112, 0
	v_mov_b32_e32 v113, 0
	v_mov_b32_e32 v114, 0
	v_mov_b32_e32 v115, 0
	v_mov_b32_e32 v116, 0
	v_mov_b32_e32 v117, 0
	v_mov_b32_e32 v118, 0
	v_mov_b32_e32 v119, 0
	v_mov_b32_e32 v120, 0
	v_mov_b32_e32 v121, 0
	v_mov_b32_e32 v122, 0
	v_mov_b32_e32 v123, 0
	v_mov_b32_e32 v124, 0
	v_mov_b32_e32 v125, 0
	v_mov_b32_e32 v126, 0
	v_mov_b32_e32 v127, 0
	v_mov_b32_e32 v128, 0
	v_mov_b32_e32 v129, 0
	s_add_i32 m0, s39, 0x0
	s_nop 0
	global_load_lds_dwordx4 v244, s[18:19]
	s_add_i32 m0, s39, 0x400
	s_nop 0
	global_load_lds_dwordx4 v245, s[18:19]
	s_add_i32 m0, s47, 0x0
	s_nop 0
	global_load_lds_dwordx4 v246, s[20:21]
	s_add_i32 m0, s47, 0x400
	s_nop 0
	global_load_lds_dwordx4 v247, s[20:21]
	s_add_i32 m0, s47, 0x800
	s_nop 0
	global_load_lds_dwordx4 v248, s[20:21]
	s_add_i32 m0, s47, 0xc00
	s_nop 0
	global_load_lds_dwordx4 v249, s[20:21]
	s_add_u32 s18, s18, 0x40000
	s_addc_u32 s19, s19, 0
	s_add_u32 s20, s20, 0x40000
	s_addc_u32 s21, s21, 0
	s_add_i32 m0, s39, 0xc000
	s_nop 0
	global_load_lds_dwordx4 v244, s[18:19]
	s_add_i32 m0, s39, 0xc400
	s_nop 0
	global_load_lds_dwordx4 v245, s[18:19]
	s_add_i32 m0, s47, 0xc000
	s_nop 0
	global_load_lds_dwordx4 v246, s[20:21]
	s_add_i32 m0, s47, 0xc400
	s_nop 0
	global_load_lds_dwordx4 v247, s[20:21]
	s_add_i32 m0, s47, 0xc800
	s_nop 0
	global_load_lds_dwordx4 v248, s[20:21]
	s_add_i32 m0, s47, 0xcc00
	s_nop 0
	global_load_lds_dwordx4 v249, s[20:21]
	s_add_u32 s18, s18, 0x40000
	s_addc_u32 s19, s19, 0
	s_add_u32 s20, s20, 0x40000
	s_addc_u32 s21, s21, 0
	s_waitcnt vmcnt(0)
	s_barrier
.Lam_loop:
	ds_read_b128 v[212:215], v228 offset:0
	ds_read_b128 v[216:219], v228 offset:8192
	ds_read_b128 v[220:223], v229 offset:0
	ds_read_b128 v[224:227], v229 offset:8192
	s_waitcnt lgkmcnt(2)
	v_mfma_f32_32x32x16_bf16 v[162:177], v[212:215], v[130:133], 0
	v_mfma_f32_32x32x16_bf16 v[178:193], v[216:219], v[130:133], 0
	ds_read_b128 v[212:215], v230 offset:0
	ds_read_b128 v[216:219], v230 offset:8192
	s_waitcnt lgkmcnt(2)
	v_mfma_f32_32x32x16_bf16 v[162:177], v[220:223], v[134:137], v[162:177]
	v_mfma_f32_32x32x16_bf16 v[178:193], v[224:227], v[134:137], v[178:193]
	ds_read_b128 v[220:223], v231 offset:0
	ds_read_b128 v[224:227], v231 offset:8192
	s_waitcnt lgkmcnt(2)
	v_mfma_f32_32x32x16_bf16 v[162:177], v[212:215], v[138:141], v[162:177]
	v_mfma_f32_32x32x16_bf16 v[178:193], v[216:219], v[138:141], v[178:193]
	ds_read_b128 v[212:215], v232 offset:0
	ds_read_b128 v[216:219], v232 offset:8192
	s_waitcnt lgkmcnt(2)
	v_mfma_f32_32x32x16_bf16 v[162:177], v[220:223], v[142:145], v[162:177]
	v_mfma_f32_32x32x16_bf16 v[178:193], v[224:227], v[142:145], v[178:193]
	ds_read_b128 v[220:223], v233 offset:0
	ds_read_b128 v[224:227], v233 offset:8192
	s_waitcnt lgkmcnt(2)
	v_mfma_f32_32x32x16_bf16 v[162:177], v[212:215], v[146:149], v[162:177]
	v_mfma_f32_32x32x16_bf16 v[178:193], v[216:219], v[146:149], v[178:193]
	ds_read_b128 v[212:215], v234 offset:0
	ds_read_b128 v[216:219], v234 offset:8192
	s_waitcnt lgkmcnt(2)
	v_mfma_f32_32x32x16_bf16 v[162:177], v[220:223], v[150:153], v[162:177]
	v_mfma_f32_32x32x16_bf16 v[178:193], v[224:227], v[150:153], v[178:193]
	ds_read_b128 v[220:223], v235 offset:0
	ds_read_b128 v[224:227], v235 offset:8192
	s_waitcnt lgkmcnt(2)
	v_mfma_f32_32x32x16_bf16 v[162:177], v[212:215], v[154:157], v[162:177]
	v_mfma_f32_32x32x16_bf16 v[178:193], v[216:219], v[154:157], v[178:193]
	s_waitcnt lgkmcnt(0)
	v_mfma_f32_32x32x16_bf16 v[162:177], v[220:223], v[158:161], v[162:177]
	v_mfma_f32_32x32x16_bf16 v[178:193], v[224:227], v[158:161], v[178:193]
	s_nop 7
	s_nop 4
	v_max_f32_e32 v240, v162, v163
	v_max3_f32 v240, v240, v164, v165
	v_max3_f32 v240, v240, v166, v167
	v_max3_f32 v240, v240, v168, v169
	v_max3_f32 v240, v240, v170, v171
	v_max3_f32 v240, v240, v172, v173
	v_max3_f32 v240, v240, v174, v175
	v_max3_f32 v240, v240, v176, v177
	v_max3_f32 v240, v240, v178, v179
	v_max3_f32 v240, v240, v180, v181
	v_max3_f32 v240, v240, v182, v183
	v_max3_f32 v240, v240, v184, v185
	v_max3_f32 v240, v240, v186, v187
	v_max3_f32 v240, v240, v188, v189
	v_max3_f32 v240, v240, v190, v191
	v_max3_f32 v240, v240, v192, v193
	v_mov_b32_e32 v241, v240
	s_nop 1
	v_permlane32_swap_b32_e32 v240, v241
	v_max_f32_e32 v240, v240, v241
	v_sub_f32_e32 v241, v240, v238
	v_cmp_ge_f32_e32 vcc, 0x42b504f3, v241
	s_nop 3
	s_cmp_eq_u64 vcc, exec
	s_cbranch_scc1 .Lam_keep_a
	v_max_f32_e32 v240, v238, v240
	v_sub_f32_e32 v241, v238, v240
	v_mul_f32_e32 v241, 0x3e0293ee, v241
	v_exp_f32_e32 v242, v241
	v_mov_b32_e32 v238, v240
	s_nop 0
	v_mul_f32_e32 v239, v239, v242
	v_pk_mul_f32 v[0:1], v[0:1], v[242:243] op_sel_hi:[1,0]
	v_pk_mul_f32 v[2:3], v[2:3], v[242:243] op_sel_hi:[1,0]
	v_pk_mul_f32 v[4:5], v[4:5], v[242:243] op_sel_hi:[1,0]
	v_pk_mul_f32 v[6:7], v[6:7], v[242:243] op_sel_hi:[1,0]
	v_pk_mul_f32 v[8:9], v[8:9], v[242:243] op_sel_hi:[1,0]
	v_pk_mul_f32 v[10:11], v[10:11], v[242:243] op_sel_hi:[1,0]
	v_pk_mul_f32 v[12:13], v[12:13], v[242:243] op_sel_hi:[1,0]
	v_pk_mul_f32 v[14:15], v[14:15], v[242:243] op_sel_hi:[1,0]
	v_pk_mul_f32 v[16:17], v[16:17], v[242:243] op_sel_hi:[1,0]
	v_pk_mul_f32 v[18:19], v[18:19], v[242:243] op_sel_hi:[1,0]
	v_pk_mul_f32 v[20:21], v[20:21], v[242:243] op_sel_hi:[1,0]
	v_pk_mul_f32 v[22:23], v[22:23], v[242:243] op_sel_hi:[1,0]
	v_pk_mul_f32 v[24:25], v[24:25], v[242:243] op_sel_hi:[1,0]
	v_pk_mul_f32 v[26:27], v[26:27], v[242:243] op_sel_hi:[1,0]
	v_pk_mul_f32 v[28:29], v[28:29], v[242:243] op_sel_hi:[1,0]
	v_pk_mul_f32 v[30:31], v[30:31], v[242:243] op_sel_hi:[1,0]
	v_pk_mul_f32 v[32:33], v[32:33], v[242:243] op_sel_hi:[1,0]
	v_pk_mul_f32 v[34:35], v[34:35], v[242:243] op_sel_hi:[1,0]
	v_pk_mul_f32 v[36:37], v[36:37], v[242:243] op_sel_hi:[1,0]
	v_pk_mul_f32 v[38:39], v[38:39], v[242:243] op_sel_hi:[1,0]
	v_pk_mul_f32 v[40:41], v[40:41], v[242:243] op_sel_hi:[1,0]
	v_pk_mul_f32 v[42:43], v[42:43], v[242:243] op_sel_hi:[1,0]
	v_pk_mul_f32 v[44:45], v[44:45], v[242:243] op_sel_hi:[1,0]
	v_pk_mul_f32 v[46:47], v[46:47], v[242:243] op_sel_hi:[1,0]
	v_pk_mul_f32 v[48:49], v[48:49], v[242:243] op_sel_hi:[1,0]
	v_pk_mul_f32 v[50:51], v[50:51], v[242:243] op_sel_hi:[1,0]
	v_pk_mul_f32 v[52:53], v[52:53], v[242:243] op_sel_hi:[1,0]
	v_pk_mul_f32 v[54:55], v[54:55], v[242:243] op_sel_hi:[1,0]
	v_pk_mul_f32 v[56:57], v[56:57], v[242:243] op_sel_hi:[1,0]
	v_pk_mul_f32 v[58:59], v[58:59], v[242:243] op_sel_hi:[1,0]
	v_pk_mul_f32 v[60:61], v[60:61], v[242:243] op_sel_hi:[1,0]
	v_pk_mul_f32 v[62:63], v[62:63], v[242:243] op_sel_hi:[1,0]
	v_pk_mul_f32 v[64:65], v[64:65], v[242:243] op_sel_hi:[1,0]
	v_pk_mul_f32 v[66:67], v[66:67], v[242:243] op_sel_hi:[1,0]
	v_pk_mul_f32 v[68:69], v[68:69], v[242:243] op_sel_hi:[1,0]
	v_pk_mul_f32 v[70:71], v[70:71], v[242:243] op_sel_hi:[1,0]
	v_pk_mul_f32 v[72:73], v[72:73], v[242:243] op_sel_hi:[1,0]
	v_pk_mul_f32 v[74:75], v[74:75], v[242:243] op_sel_hi:[1,0]
	v_pk_mul_f32 v[76:77], v[76:77], v[242:243] op_sel_hi:[1,0]
	v_pk_mul_f32 v[78:79], v[78:79], v[242:243] op_sel_hi:[1,0]
	v_pk_mul_f32 v[80:81], v[80:81], v[242:243] op_sel_hi:[1,0]
	v_pk_mul_f32 v[82:83], v[82:83], v[242:243] op_sel_hi:[1,0]
	v_pk_mul_f32 v[84:85], v[84:85], v[242:243] op_sel_hi:[1,0]
	v_pk_mul_f32 v[86:87], v[86:87], v[242:243] op_sel_hi:[1,0]
	v_pk_mul_f32 v[88:89], v[88:89], v[242:243] op_sel_hi:[1,0]
	v_pk_mul_f32 v[90:91], v[90:91], v[242:243] op_sel_hi:[1,0]
	v_pk_mul_f32 v[92:93], v[92:93], v[242:243] op_sel_hi:[1,0]
	v_pk_mul_f32 v[94:95], v[94:95], v[242:243] op_sel_hi:[1,0]
	v_pk_mul_f32 v[98:99], v[98:99], v[242:243] op_sel_hi:[1,0]
	v_pk_mul_f32 v[100:101], v[100:101], v[242:243] op_sel_hi:[1,0]
	v_pk_mul_f32 v[102:103], v[102:103], v[242:243] op_sel_hi:[1,0]
	v_pk_mul_f32 v[104:105], v[104:105], v[242:243] op_sel_hi:[1,0]
	v_pk_mul_f32 v[106:107], v[106:107], v[242:243] op_sel_hi:[1,0]
	v_pk_mul_f32 v[108:109], v[108:109], v[242:243] op_sel_hi:[1,0]
	v_pk_mul_f32 v[110:111], v[110:111], v[242:243] op_sel_hi:[1,0]
	v_pk_mul_f32 v[112:113], v[112:113], v[242:243] op_sel_hi:[1,0]
	v_pk_mul_f32 v[114:115], v[114:115], v[242:243] op_sel_hi:[1,0]
	v_pk_mul_f32 v[116:117], v[116:117], v[242:243] op_sel_hi:[1,0]
	v_pk_mul_f32 v[118:119], v[118:119], v[242:243] op_sel_hi:[1,0]
	v_pk_mul_f32 v[120:121], v[120:121], v[242:243] op_sel_hi:[1,0]
	v_pk_mul_f32 v[122:123], v[122:123], v[242:243] op_sel_hi:[1,0]
	v_pk_mul_f32 v[124:125], v[124:125], v[242:243] op_sel_hi:[1,0]
	v_pk_mul_f32 v[126:127], v[126:127], v[242:243] op_sel_hi:[1,0]
	v_pk_mul_f32 v[128:129], v[128:129], v[242:243] op_sel_hi:[1,0]
.Lam_keep_a:
	v_mul_f32_e32 v243, 0xbe0293ee, v238
	v_fmamk_f32 v162, v162, 0x3e0293ee, v243
	v_fmamk_f32 v163, v163, 0x3e0293ee, v243
	v_fmamk_f32 v164, v164, 0x3e0293ee, v243
	v_fmamk_f32 v165, v165, 0x3e0293ee, v243
	v_fmamk_f32 v166, v166, 0x3e0293ee, v243
	v_fmamk_f32 v167, v167, 0x3e0293ee, v243
	v_fmamk_f32 v168, v168, 0x3e0293ee, v243
	v_fmamk_f32 v169, v169, 0x3e0293ee, v243
	v_fmamk_f32 v170, v170, 0x3e0293ee, v243
	v_fmamk_f32 v171, v171, 0x3e0293ee, v243
	v_fmamk_f32 v172, v172, 0x3e0293ee, v243
	v_fmamk_f32 v173, v173, 0x3e0293ee, v243
	v_fmamk_f32 v174, v174, 0x3e0293ee, v243
	v_fmamk_f32 v175, v175, 0x3e0293ee, v243
	v_fmamk_f32 v176, v176, 0x3e0293ee, v243
	v_fmamk_f32 v177, v177, 0x3e0293ee, v243
	v_fmamk_f32 v178, v178, 0x3e0293ee, v243
	v_fmamk_f32 v179, v179, 0x3e0293ee, v243
	v_fmamk_f32 v180, v180, 0x3e0293ee, v243
	v_fmamk_f32 v181, v181, 0x3e0293ee, v243
	v_fmamk_f32 v182, v182, 0x3e0293ee, v243
	v_fmamk_f32 v183, v183, 0x3e0293ee, v243
	v_fmamk_f32 v184, v184, 0x3e0293ee, v243
	v_fmamk_f32 v185, v185, 0x3e0293ee, v243
	v_fmamk_f32 v186, v186, 0x3e0293ee, v243
	v_fmamk_f32 v187, v187, 0x3e0293ee, v243
	v_fmamk_f32 v188, v188, 0x3e0293ee, v243
	v_fmamk_f32 v189, v189, 0x3e0293ee, v243
	v_fmamk_f32 v190, v190, 0x3e0293ee, v243
	v_fmamk_f32 v191, v191, 0x3e0293ee, v243
	v_fmamk_f32 v192, v192, 0x3e0293ee, v243
	v_fmamk_f32 v193, v193, 0x3e0293ee, v243
	v_exp_f32_e32 v162, v162
	v_exp_f32_e32 v163, v163
	v_exp_f32_e32 v164, v164
	v_exp_f32_e32 v165, v165
	v_exp_f32_e32 v166, v166
	v_exp_f32_e32 v167, v167
	v_exp_f32_e32 v168, v168
	v_exp_f32_e32 v169, v169
	v_exp_f32_e32 v170, v170
	v_exp_f32_e32 v171, v171
	v_exp_f32_e32 v172, v172
	v_exp_f32_e32 v173, v173
	v_exp_f32_e32 v174, v174
	v_exp_f32_e32 v175, v175
	v_exp_f32_e32 v176, v176
	v_exp_f32_e32 v177, v177
	v_exp_f32_e32 v178, v178
	v_exp_f32_e32 v179, v179
	v_exp_f32_e32 v180, v180
	v_exp_f32_e32 v181, v181
	v_exp_f32_e32 v182, v182
	v_exp_f32_e32 v183, v183
	v_exp_f32_e32 v184, v184
	v_exp_f32_e32 v185, v185
	v_exp_f32_e32 v186, v186
	v_exp_f32_e32 v187, v187
	v_exp_f32_e32 v188, v188
	v_exp_f32_e32 v189, v189
	v_exp_f32_e32 v190, v190
	v_exp_f32_e32 v191, v191
	v_exp_f32_e32 v192, v192
	v_exp_f32_e32 v193, v193
	v_add_f32_e32 v240, v162, v163
	v_add_f32_e32 v240, v240, v164
	v_add_f32_e32 v240, v240, v165
	v_add_f32_e32 v240, v240, v166
	v_add_f32_e32 v240, v240, v167
	v_add_f32_e32 v240, v240, v168
	v_add_f32_e32 v240, v240, v169
	v_add_f32_e32 v240, v240, v170
	v_add_f32_e32 v240, v240, v171
	v_add_f32_e32 v240, v240, v172
	v_add_f32_e32 v240, v240, v173
	v_add_f32_e32 v240, v240, v174
	v_add_f32_e32 v240, v240, v175
	v_add_f32_e32 v240, v240, v176
	v_add_f32_e32 v240, v240, v177
	v_add_f32_e32 v240, v240, v178
	v_add_f32_e32 v240, v240, v179
	v_add_f32_e32 v240, v240, v180
	v_add_f32_e32 v240, v240, v181
	v_add_f32_e32 v240, v240, v182
	v_add_f32_e32 v240, v240, v183
	v_add_f32_e32 v240, v240, v184
	v_add_f32_e32 v240, v240, v185
	v_add_f32_e32 v240, v240, v186
	v_add_f32_e32 v240, v240, v187
	v_add_f32_e32 v240, v240, v188
	v_add_f32_e32 v240, v240, v189
	v_add_f32_e32 v240, v240, v190
	v_add_f32_e32 v240, v240, v191
	v_add_f32_e32 v240, v240, v192
	v_add_f32_e32 v240, v240, v193
	v_mov_b32_e32 v241, v240
	v_cvt_pk_bf16_f32 v196, v162, v163
	v_cvt_pk_bf16_f32 v197, v164, v165
	v_cvt_pk_bf16_f32 v198, v166, v167
	v_cvt_pk_bf16_f32 v199, v168, v169
	v_cvt_pk_bf16_f32 v200, v170, v171
	v_cvt_pk_bf16_f32 v201, v172, v173
	v_cvt_pk_bf16_f32 v202, v174, v175
	v_cvt_pk_bf16_f32 v203, v176, v177
	v_cvt_pk_bf16_f32 v204, v178, v179
	v_cvt_pk_bf16_f32 v205, v180, v181
	v_cvt_pk_bf16_f32 v206, v182, v183
	v_cvt_pk_bf16_f32 v207, v184, v185
	v_cvt_pk_bf16_f32 v208, v186, v187
	v_cvt_pk_bf16_f32 v209, v188, v189
	v_cvt_pk_bf16_f32 v210, v190, v191
	v_cvt_pk_bf16_f32 v211, v192, v193
	s_nop 1
	v_permlane32_swap_b32_e32 v240, v241
	v_permlane32_swap_b32_e32 v196, v198
	v_permlane32_swap_b32_e32 v197, v199
	v_permlane32_swap_b32_e32 v200, v202
	v_permlane32_swap_b32_e32 v201, v203
	v_permlane32_swap_b32_e32 v204, v206
	v_permlane32_swap_b32_e32 v205, v207
	v_permlane32_swap_b32_e32 v208, v210
	v_permlane32_swap_b32_e32 v209, v211
	v_add_f32_e32 v240, v240, v241
	v_add_f32_e32 v239, v239, v240
	ds_read_b64_tr_b16 v[162:163], v236 offset:0
	ds_read_b64_tr_b16 v[164:165], v236 offset:4096
	ds_read_b64_tr_b16 v[166:167], v236 offset:8192
	ds_read_b64_tr_b16 v[168:169], v236 offset:12288
	ds_read_b64_tr_b16 v[170:171], v236 offset:16384
	ds_read_b64_tr_b16 v[172:173], v236 offset:20480
	ds_read_b64_tr_b16 v[174:175], v236 offset:24576
	ds_read_b64_tr_b16 v[176:177], v236 offset:28672
	ds_read_b64_tr_b16 v[178:179], v236 offset:512
	ds_read_b64_tr_b16 v[180:181], v236 offset:4608
	ds_read_b64_tr_b16 v[182:183], v236 offset:8704
	ds_read_b64_tr_b16 v[184:185], v236 offset:12800
	ds_read_b64_tr_b16 v[186:187], v236 offset:16896
	ds_read_b64_tr_b16 v[188:189], v236 offset:20992
	ds_read_b64_tr_b16 v[190:191], v236 offset:25088
	ds_read_b64_tr_b16 v[192:193], v236 offset:29184
	s_waitcnt lgkmcnt(8)
	v_mfma_f32_32x32x16_bf16 v[0:15], v[162:165], v[196:199], v[0:15]
	v_mfma_f32_32x32x16_bf16 v[0:15], v[166:169], v[200:203], v[0:15]
	v_mfma_f32_32x32x16_bf16 v[0:15], v[170:173], v[204:207], v[0:15]
	v_mfma_f32_32x32x16_bf16 v[0:15], v[174:177], v[208:211], v[0:15]
	ds_read_b64_tr_b16 v[162:163], v236 offset:1024
	ds_read_b64_tr_b16 v[164:165], v236 offset:5120
	ds_read_b64_tr_b16 v[166:167], v236 offset:9216
	ds_read_b64_tr_b16 v[168:169], v236 offset:13312
	ds_read_b64_tr_b16 v[170:171], v236 offset:17408
	ds_read_b64_tr_b16 v[172:173], v236 offset:21504
	ds_read_b64_tr_b16 v[174:175], v236 offset:25600
	ds_read_b64_tr_b16 v[176:177], v236 offset:29696
	s_waitcnt lgkmcnt(8)
	v_mfma_f32_32x32x16_bf16 v[16:31], v[178:181], v[196:199], v[16:31]
	v_mfma_f32_32x32x16_bf16 v[16:31], v[182:185], v[200:203], v[16:31]
	v_mfma_f32_32x32x16_bf16 v[16:31], v[186:189], v[204:207], v[16:31]
	v_mfma_f32_32x32x16_bf16 v[16:31], v[190:193], v[208:211], v[16:31]
	ds_read_b64_tr_b16 v[178:179], v236 offset:1536
	ds_read_b64_tr_b16 v[180:181], v236 offset:5632
	ds_read_b64_tr_b16 v[182:183], v236 offset:9728
	ds_read_b64_tr_b16 v[184:185], v236 offset:13824
	ds_read_b64_tr_b16 v[186:187], v236 offset:17920
	ds_read_b64_tr_b16 v[188:189], v236 offset:22016
	ds_read_b64_tr_b16 v[190:191], v236 offset:26112
	ds_read_b64_tr_b16 v[192:193], v236 offset:30208
	s_waitcnt lgkmcnt(8)
	v_mfma_f32_32x32x16_bf16 v[32:47], v[162:165], v[196:199], v[32:47]
	v_mfma_f32_32x32x16_bf16 v[32:47], v[166:169], v[200:203], v[32:47]
	v_mfma_f32_32x32x16_bf16 v[32:47], v[170:173], v[204:207], v[32:47]
	v_mfma_f32_32x32x16_bf16 v[32:47], v[174:177], v[208:211], v[32:47]
	ds_read_b64_tr_b16 v[162:163], v236 offset:2048
	ds_read_b64_tr_b16 v[164:165], v236 offset:6144
	ds_read_b64_tr_b16 v[166:167], v236 offset:10240
	ds_read_b64_tr_b16 v[168:169], v236 offset:14336
	ds_read_b64_tr_b16 v[170:171], v236 offset:18432
	ds_read_b64_tr_b16 v[172:173], v236 offset:22528
	ds_read_b64_tr_b16 v[174:175], v236 offset:26624
	ds_read_b64_tr_b16 v[176:177], v236 offset:30720
	s_waitcnt lgkmcnt(8)
	v_mfma_f32_32x32x16_bf16 v[48:63], v[178:181], v[196:199], v[48:63]
	v_mfma_f32_32x32x16_bf16 v[48:63], v[182:185], v[200:203], v[48:63]
	v_mfma_f32_32x32x16_bf16 v[48:63], v[186:189], v[204:207], v[48:63]
	v_mfma_f32_32x32x16_bf16 v[48:63], v[190:193], v[208:211], v[48:63]
	ds_read_b64_tr_b16 v[178:179], v236 offset:2560
	ds_read_b64_tr_b16 v[180:181], v236 offset:6656
	ds_read_b64_tr_b16 v[182:183], v236 offset:10752
	ds_read_b64_tr_b16 v[184:185], v236 offset:14848
	ds_read_b64_tr_b16 v[186:187], v236 offset:18944
	ds_read_b64_tr_b16 v[188:189], v236 offset:23040
	ds_read_b64_tr_b16 v[190:191], v236 offset:27136
	ds_read_b64_tr_b16 v[192:193], v236 offset:31232
	s_waitcnt lgkmcnt(8)
	v_mfma_f32_32x32x16_bf16 v[64:79], v[162:165], v[196:199], v[64:79]
	v_mfma_f32_32x32x16_bf16 v[64:79], v[166:169], v[200:203], v[64:79]
	v_mfma_f32_32x32x16_bf16 v[64:79], v[170:173], v[204:207], v[64:79]
	v_mfma_f32_32x32x16_bf16 v[64:79], v[174:177], v[208:211], v[64:79]
	ds_read_b64_tr_b16 v[162:163], v236 offset:3072
	ds_read_b64_tr_b16 v[164:165], v236 offset:7168
	ds_read_b64_tr_b16 v[166:167], v236 offset:11264
	ds_read_b64_tr_b16 v[168:169], v236 offset:15360
	ds_read_b64_tr_b16 v[170:171], v236 offset:19456
	ds_read_b64_tr_b16 v[172:173], v236 offset:23552
	ds_read_b64_tr_b16 v[174:175], v236 offset:27648
	ds_read_b64_tr_b16 v[176:177], v236 offset:31744
	s_waitcnt lgkmcnt(8)
	v_mfma_f32_32x32x16_bf16 v[80:95], v[178:181], v[196:199], v[80:95]
	v_mfma_f32_32x32x16_bf16 v[80:95], v[182:185], v[200:203], v[80:95]
	v_mfma_f32_32x32x16_bf16 v[80:95], v[186:189], v[204:207], v[80:95]
	v_mfma_f32_32x32x16_bf16 v[80:95], v[190:193], v[208:211], v[80:95]
	ds_read_b64_tr_b16 v[178:179], v236 offset:3584
	ds_read_b64_tr_b16 v[180:181], v236 offset:7680
	ds_read_b64_tr_b16 v[182:183], v236 offset:11776
	ds_read_b64_tr_b16 v[184:185], v236 offset:15872
	ds_read_b64_tr_b16 v[186:187], v236 offset:19968
	ds_read_b64_tr_b16 v[188:189], v236 offset:24064
	ds_read_b64_tr_b16 v[190:191], v236 offset:28160
	ds_read_b64_tr_b16 v[192:193], v236 offset:32256
	s_waitcnt lgkmcnt(8)
	v_mfma_f32_32x32x16_bf16 v[98:113], v[162:165], v[196:199], v[98:113]
	v_mfma_f32_32x32x16_bf16 v[98:113], v[166:169], v[200:203], v[98:113]
	v_mfma_f32_32x32x16_bf16 v[98:113], v[170:173], v[204:207], v[98:113]
	v_mfma_f32_32x32x16_bf16 v[98:113], v[174:177], v[208:211], v[98:113]
	s_waitcnt lgkmcnt(0)
	v_mfma_f32_32x32x16_bf16 v[114:129], v[178:181], v[196:199], v[114:129]
	v_mfma_f32_32x32x16_bf16 v[114:129], v[182:185], v[200:203], v[114:129]
	v_mfma_f32_32x32x16_bf16 v[114:129], v[186:189], v[204:207], v[114:129]
	v_mfma_f32_32x32x16_bf16 v[114:129], v[190:193], v[208:211], v[114:129]
	s_waitcnt vmcnt(0)
	s_barrier
	s_cmp_le_u32 s13, 2
	s_cbranch_scc1 .Lam_nodma_a
	s_add_i32 m0, s39, 0x0
	s_nop 0
	global_load_lds_dwordx4 v244, s[18:19]
	s_add_i32 m0, s39, 0x400
	s_nop 0
	global_load_lds_dwordx4 v245, s[18:19]
	s_add_i32 m0, s47, 0x0
	s_nop 0
	global_load_lds_dwordx4 v246, s[20:21]
	s_add_i32 m0, s47, 0x400
	s_nop 0
	global_load_lds_dwordx4 v247, s[20:21]
	s_add_i32 m0, s47, 0x800
	s_nop 0
	global_load_lds_dwordx4 v248, s[20:21]
	s_add_i32 m0, s47, 0xc00
	s_nop 0
	global_load_lds_dwordx4 v249, s[20:21]
	s_add_u32 s18, s18, 0x40000
	s_addc_u32 s19, s19, 0
	s_add_u32 s20, s20, 0x40000
	s_addc_u32 s21, s21, 0
.Lam_nodma_a:
	ds_read_b128 v[212:215], v228 offset:49152
	ds_read_b128 v[216:219], v228 offset:57344
	ds_read_b128 v[220:223], v229 offset:49152
	ds_read_b128 v[224:227], v229 offset:57344
	s_waitcnt lgkmcnt(2)
	v_mfma_f32_32x32x16_bf16 v[162:177], v[212:215], v[130:133], 0
	v_mfma_f32_32x32x16_bf16 v[178:193], v[216:219], v[130:133], 0
	ds_read_b128 v[212:215], v230 offset:49152
	ds_read_b128 v[216:219], v230 offset:57344
	s_waitcnt lgkmcnt(2)
	v_mfma_f32_32x32x16_bf16 v[162:177], v[220:223], v[134:137], v[162:177]
	v_mfma_f32_32x32x16_bf16 v[178:193], v[224:227], v[134:137], v[178:193]
	ds_read_b128 v[220:223], v231 offset:49152
	ds_read_b128 v[224:227], v231 offset:57344
	s_waitcnt lgkmcnt(2)
	v_mfma_f32_32x32x16_bf16 v[162:177], v[212:215], v[138:141], v[162:177]
	v_mfma_f32_32x32x16_bf16 v[178:193], v[216:219], v[138:141], v[178:193]
	ds_read_b128 v[212:215], v232 offset:49152
	ds_read_b128 v[216:219], v232 offset:57344
	s_waitcnt lgkmcnt(2)
	v_mfma_f32_32x32x16_bf16 v[162:177], v[220:223], v[142:145], v[162:177]
	v_mfma_f32_32x32x16_bf16 v[178:193], v[224:227], v[142:145], v[178:193]
	ds_read_b128 v[220:223], v233 offset:49152
	ds_read_b128 v[224:227], v233 offset:57344
	s_waitcnt lgkmcnt(2)
	v_mfma_f32_32x32x16_bf16 v[162:177], v[212:215], v[146:149], v[162:177]
	v_mfma_f32_32x32x16_bf16 v[178:193], v[216:219], v[146:149], v[178:193]
	ds_read_b128 v[212:215], v234 offset:49152
	ds_read_b128 v[216:219], v234 offset:57344
	s_waitcnt lgkmcnt(2)
	v_mfma_f32_32x32x16_bf16 v[162:177], v[220:223], v[150:153], v[162:177]
	v_mfma_f32_32x32x16_bf16 v[178:193], v[224:227], v[150:153], v[178:193]
	ds_read_b128 v[220:223], v235 offset:49152
	ds_read_b128 v[224:227], v235 offset:57344
	s_waitcnt lgkmcnt(2)
	v_mfma_f32_32x32x16_bf16 v[162:177], v[212:215], v[154:157], v[162:177]
	v_mfma_f32_32x32x16_bf16 v[178:193], v[216:219], v[154:157], v[178:193]
	s_waitcnt lgkmcnt(0)
	v_mfma_f32_32x32x16_bf16 v[162:177], v[220:223], v[158:161], v[162:177]
	v_mfma_f32_32x32x16_bf16 v[178:193], v[224:227], v[158:161], v[178:193]
	s_nop 7
	s_nop 4
	v_max_f32_e32 v240, v162, v163
	v_max3_f32 v240, v240, v164, v165
	v_max3_f32 v240, v240, v166, v167
	v_max3_f32 v240, v240, v168, v169
	v_max3_f32 v240, v240, v170, v171
	v_max3_f32 v240, v240, v172, v173
	v_max3_f32 v240, v240, v174, v175
	v_max3_f32 v240, v240, v176, v177
	v_max3_f32 v240, v240, v178, v179
	v_max3_f32 v240, v240, v180, v181
	v_max3_f32 v240, v240, v182, v183
	v_max3_f32 v240, v240, v184, v185
	v_max3_f32 v240, v240, v186, v187
	v_max3_f32 v240, v240, v188, v189
	v_max3_f32 v240, v240, v190, v191
	v_max3_f32 v240, v240, v192, v193
	v_mov_b32_e32 v241, v240
	s_nop 1
	v_permlane32_swap_b32_e32 v240, v241
	v_max_f32_e32 v240, v240, v241
	v_sub_f32_e32 v241, v240, v238
	v_cmp_ge_f32_e32 vcc, 0x42b504f3, v241
	s_nop 3
	s_cmp_eq_u64 vcc, exec
	s_cbranch_scc1 .Lam_keep_b
	v_max_f32_e32 v240, v238, v240
	v_sub_f32_e32 v241, v238, v240
	v_mul_f32_e32 v241, 0x3e0293ee, v241
	v_exp_f32_e32 v242, v241
	v_mov_b32_e32 v238, v240
	s_nop 0
	v_mul_f32_e32 v239, v239, v242
	v_pk_mul_f32 v[0:1], v[0:1], v[242:243] op_sel_hi:[1,0]
	v_pk_mul_f32 v[2:3], v[2:3], v[242:243] op_sel_hi:[1,0]
	v_pk_mul_f32 v[4:5], v[4:5], v[242:243] op_sel_hi:[1,0]
	v_pk_mul_f32 v[6:7], v[6:7], v[242:243] op_sel_hi:[1,0]
	v_pk_mul_f32 v[8:9], v[8:9], v[242:243] op_sel_hi:[1,0]
	v_pk_mul_f32 v[10:11], v[10:11], v[242:243] op_sel_hi:[1,0]
	v_pk_mul_f32 v[12:13], v[12:13], v[242:243] op_sel_hi:[1,0]
	v_pk_mul_f32 v[14:15], v[14:15], v[242:243] op_sel_hi:[1,0]
	v_pk_mul_f32 v[16:17], v[16:17], v[242:243] op_sel_hi:[1,0]
	v_pk_mul_f32 v[18:19], v[18:19], v[242:243] op_sel_hi:[1,0]
	v_pk_mul_f32 v[20:21], v[20:21], v[242:243] op_sel_hi:[1,0]
	v_pk_mul_f32 v[22:23], v[22:23], v[242:243] op_sel_hi:[1,0]
	v_pk_mul_f32 v[24:25], v[24:25], v[242:243] op_sel_hi:[1,0]
	v_pk_mul_f32 v[26:27], v[26:27], v[242:243] op_sel_hi:[1,0]
	v_pk_mul_f32 v[28:29], v[28:29], v[242:243] op_sel_hi:[1,0]
	v_pk_mul_f32 v[30:31], v[30:31], v[242:243] op_sel_hi:[1,0]
	v_pk_mul_f32 v[32:33], v[32:33], v[242:243] op_sel_hi:[1,0]
	v_pk_mul_f32 v[34:35], v[34:35], v[242:243] op_sel_hi:[1,0]
	v_pk_mul_f32 v[36:37], v[36:37], v[242:243] op_sel_hi:[1,0]
	v_pk_mul_f32 v[38:39], v[38:39], v[242:243] op_sel_hi:[1,0]
	v_pk_mul_f32 v[40:41], v[40:41], v[242:243] op_sel_hi:[1,0]
	v_pk_mul_f32 v[42:43], v[42:43], v[242:243] op_sel_hi:[1,0]
	v_pk_mul_f32 v[44:45], v[44:45], v[242:243] op_sel_hi:[1,0]
	v_pk_mul_f32 v[46:47], v[46:47], v[242:243] op_sel_hi:[1,0]
	v_pk_mul_f32 v[48:49], v[48:49], v[242:243] op_sel_hi:[1,0]
	v_pk_mul_f32 v[50:51], v[50:51], v[242:243] op_sel_hi:[1,0]
	v_pk_mul_f32 v[52:53], v[52:53], v[242:243] op_sel_hi:[1,0]
	v_pk_mul_f32 v[54:55], v[54:55], v[242:243] op_sel_hi:[1,0]
	v_pk_mul_f32 v[56:57], v[56:57], v[242:243] op_sel_hi:[1,0]
	v_pk_mul_f32 v[58:59], v[58:59], v[242:243] op_sel_hi:[1,0]
	v_pk_mul_f32 v[60:61], v[60:61], v[242:243] op_sel_hi:[1,0]
	v_pk_mul_f32 v[62:63], v[62:63], v[242:243] op_sel_hi:[1,0]
	v_pk_mul_f32 v[64:65], v[64:65], v[242:243] op_sel_hi:[1,0]
	v_pk_mul_f32 v[66:67], v[66:67], v[242:243] op_sel_hi:[1,0]
	v_pk_mul_f32 v[68:69], v[68:69], v[242:243] op_sel_hi:[1,0]
	v_pk_mul_f32 v[70:71], v[70:71], v[242:243] op_sel_hi:[1,0]
	v_pk_mul_f32 v[72:73], v[72:73], v[242:243] op_sel_hi:[1,0]
	v_pk_mul_f32 v[74:75], v[74:75], v[242:243] op_sel_hi:[1,0]
	v_pk_mul_f32 v[76:77], v[76:77], v[242:243] op_sel_hi:[1,0]
	v_pk_mul_f32 v[78:79], v[78:79], v[242:243] op_sel_hi:[1,0]
	v_pk_mul_f32 v[80:81], v[80:81], v[242:243] op_sel_hi:[1,0]
	v_pk_mul_f32 v[82:83], v[82:83], v[242:243] op_sel_hi:[1,0]
	v_pk_mul_f32 v[84:85], v[84:85], v[242:243] op_sel_hi:[1,0]
	v_pk_mul_f32 v[86:87], v[86:87], v[242:243] op_sel_hi:[1,0]
	v_pk_mul_f32 v[88:89], v[88:89], v[242:243] op_sel_hi:[1,0]
	v_pk_mul_f32 v[90:91], v[90:91], v[242:243] op_sel_hi:[1,0]
	v_pk_mul_f32 v[92:93], v[92:93], v[242:243] op_sel_hi:[1,0]
	v_pk_mul_f32 v[94:95], v[94:95], v[242:243] op_sel_hi:[1,0]
	v_pk_mul_f32 v[98:99], v[98:99], v[242:243] op_sel_hi:[1,0]
	v_pk_mul_f32 v[100:101], v[100:101], v[242:243] op_sel_hi:[1,0]
	v_pk_mul_f32 v[102:103], v[102:103], v[242:243] op_sel_hi:[1,0]
	v_pk_mul_f32 v[104:105], v[104:105], v[242:243] op_sel_hi:[1,0]
	v_pk_mul_f32 v[106:107], v[106:107], v[242:243] op_sel_hi:[1,0]
	v_pk_mul_f32 v[108:109], v[108:109], v[242:243] op_sel_hi:[1,0]
	v_pk_mul_f32 v[110:111], v[110:111], v[242:243] op_sel_hi:[1,0]
	v_pk_mul_f32 v[112:113], v[112:113], v[242:243] op_sel_hi:[1,0]
	v_pk_mul_f32 v[114:115], v[114:115], v[242:243] op_sel_hi:[1,0]
	v_pk_mul_f32 v[116:117], v[116:117], v[242:243] op_sel_hi:[1,0]
	v_pk_mul_f32 v[118:119], v[118:119], v[242:243] op_sel_hi:[1,0]
	v_pk_mul_f32 v[120:121], v[120:121], v[242:243] op_sel_hi:[1,0]
	v_pk_mul_f32 v[122:123], v[122:123], v[242:243] op_sel_hi:[1,0]
	v_pk_mul_f32 v[124:125], v[124:125], v[242:243] op_sel_hi:[1,0]
	v_pk_mul_f32 v[126:127], v[126:127], v[242:243] op_sel_hi:[1,0]
	v_pk_mul_f32 v[128:129], v[128:129], v[242:243] op_sel_hi:[1,0]
.Lam_keep_b:
	v_mul_f32_e32 v243, 0xbe0293ee, v238
	v_fmamk_f32 v162, v162, 0x3e0293ee, v243
	v_fmamk_f32 v163, v163, 0x3e0293ee, v243
	v_fmamk_f32 v164, v164, 0x3e0293ee, v243
	v_fmamk_f32 v165, v165, 0x3e0293ee, v243
	v_fmamk_f32 v166, v166, 0x3e0293ee, v243
	v_fmamk_f32 v167, v167, 0x3e0293ee, v243
	v_fmamk_f32 v168, v168, 0x3e0293ee, v243
	v_fmamk_f32 v169, v169, 0x3e0293ee, v243
	v_fmamk_f32 v170, v170, 0x3e0293ee, v243
	v_fmamk_f32 v171, v171, 0x3e0293ee, v243
	v_fmamk_f32 v172, v172, 0x3e0293ee, v243
	v_fmamk_f32 v173, v173, 0x3e0293ee, v243
	v_fmamk_f32 v174, v174, 0x3e0293ee, v243
	v_fmamk_f32 v175, v175, 0x3e0293ee, v243
	v_fmamk_f32 v176, v176, 0x3e0293ee, v243
	v_fmamk_f32 v177, v177, 0x3e0293ee, v243
	v_fmamk_f32 v178, v178, 0x3e0293ee, v243
	v_fmamk_f32 v179, v179, 0x3e0293ee, v243
	v_fmamk_f32 v180, v180, 0x3e0293ee, v243
	v_fmamk_f32 v181, v181, 0x3e0293ee, v243
	v_fmamk_f32 v182, v182, 0x3e0293ee, v243
	v_fmamk_f32 v183, v183, 0x3e0293ee, v243
	v_fmamk_f32 v184, v184, 0x3e0293ee, v243
	v_fmamk_f32 v185, v185, 0x3e0293ee, v243
	v_fmamk_f32 v186, v186, 0x3e0293ee, v243
	v_fmamk_f32 v187, v187, 0x3e0293ee, v243
	v_fmamk_f32 v188, v188, 0x3e0293ee, v243
	v_fmamk_f32 v189, v189, 0x3e0293ee, v243
	v_fmamk_f32 v190, v190, 0x3e0293ee, v243
	v_fmamk_f32 v191, v191, 0x3e0293ee, v243
	v_fmamk_f32 v192, v192, 0x3e0293ee, v243
	v_fmamk_f32 v193, v193, 0x3e0293ee, v243
	v_exp_f32_e32 v162, v162
	v_exp_f32_e32 v163, v163
	v_exp_f32_e32 v164, v164
	v_exp_f32_e32 v165, v165
	v_exp_f32_e32 v166, v166
	v_exp_f32_e32 v167, v167
	v_exp_f32_e32 v168, v168
	v_exp_f32_e32 v169, v169
	v_exp_f32_e32 v170, v170
	v_exp_f32_e32 v171, v171
	v_exp_f32_e32 v172, v172
	v_exp_f32_e32 v173, v173
	v_exp_f32_e32 v174, v174
	v_exp_f32_e32 v175, v175
	v_exp_f32_e32 v176, v176
	v_exp_f32_e32 v177, v177
	v_exp_f32_e32 v178, v178
	v_exp_f32_e32 v179, v179
	v_exp_f32_e32 v180, v180
	v_exp_f32_e32 v181, v181
	v_exp_f32_e32 v182, v182
	v_exp_f32_e32 v183, v183
	v_exp_f32_e32 v184, v184
	v_exp_f32_e32 v185, v185
	v_exp_f32_e32 v186, v186
	v_exp_f32_e32 v187, v187
	v_exp_f32_e32 v188, v188
	v_exp_f32_e32 v189, v189
	v_exp_f32_e32 v190, v190
	v_exp_f32_e32 v191, v191
	v_exp_f32_e32 v192, v192
	v_exp_f32_e32 v193, v193
	v_add_f32_e32 v240, v162, v163
	v_add_f32_e32 v240, v240, v164
	v_add_f32_e32 v240, v240, v165
	v_add_f32_e32 v240, v240, v166
	v_add_f32_e32 v240, v240, v167
	v_add_f32_e32 v240, v240, v168
	v_add_f32_e32 v240, v240, v169
	v_add_f32_e32 v240, v240, v170
	v_add_f32_e32 v240, v240, v171
	v_add_f32_e32 v240, v240, v172
	v_add_f32_e32 v240, v240, v173
	v_add_f32_e32 v240, v240, v174
	v_add_f32_e32 v240, v240, v175
	v_add_f32_e32 v240, v240, v176
	v_add_f32_e32 v240, v240, v177
	v_add_f32_e32 v240, v240, v178
	v_add_f32_e32 v240, v240, v179
	v_add_f32_e32 v240, v240, v180
	v_add_f32_e32 v240, v240, v181
	v_add_f32_e32 v240, v240, v182
	v_add_f32_e32 v240, v240, v183
	v_add_f32_e32 v240, v240, v184
	v_add_f32_e32 v240, v240, v185
	v_add_f32_e32 v240, v240, v186
	v_add_f32_e32 v240, v240, v187
	v_add_f32_e32 v240, v240, v188
	v_add_f32_e32 v240, v240, v189
	v_add_f32_e32 v240, v240, v190
	v_add_f32_e32 v240, v240, v191
	v_add_f32_e32 v240, v240, v192
	v_add_f32_e32 v240, v240, v193
	v_mov_b32_e32 v241, v240
	v_cvt_pk_bf16_f32 v196, v162, v163
	v_cvt_pk_bf16_f32 v197, v164, v165
	v_cvt_pk_bf16_f32 v198, v166, v167
	v_cvt_pk_bf16_f32 v199, v168, v169
	v_cvt_pk_bf16_f32 v200, v170, v171
	v_cvt_pk_bf16_f32 v201, v172, v173
	v_cvt_pk_bf16_f32 v202, v174, v175
	v_cvt_pk_bf16_f32 v203, v176, v177
	v_cvt_pk_bf16_f32 v204, v178, v179
	v_cvt_pk_bf16_f32 v205, v180, v181
	v_cvt_pk_bf16_f32 v206, v182, v183
	v_cvt_pk_bf16_f32 v207, v184, v185
	v_cvt_pk_bf16_f32 v208, v186, v187
	v_cvt_pk_bf16_f32 v209, v188, v189
	v_cvt_pk_bf16_f32 v210, v190, v191
	v_cvt_pk_bf16_f32 v211, v192, v193
	s_nop 1
	v_permlane32_swap_b32_e32 v240, v241
	v_permlane32_swap_b32_e32 v196, v198
	v_permlane32_swap_b32_e32 v197, v199
	v_permlane32_swap_b32_e32 v200, v202
	v_permlane32_swap_b32_e32 v201, v203
	v_permlane32_swap_b32_e32 v204, v206
	v_permlane32_swap_b32_e32 v205, v207
	v_permlane32_swap_b32_e32 v208, v210
	v_permlane32_swap_b32_e32 v209, v211
	v_add_f32_e32 v240, v240, v241
	v_add_f32_e32 v239, v239, v240
	ds_read_b64_tr_b16 v[162:163], v237 offset:0
	ds_read_b64_tr_b16 v[164:165], v237 offset:4096
	ds_read_b64_tr_b16 v[166:167], v237 offset:8192
	ds_read_b64_tr_b16 v[168:169], v237 offset:12288
	ds_read_b64_tr_b16 v[170:171], v237 offset:16384
	ds_read_b64_tr_b16 v[172:173], v237 offset:20480
	ds_read_b64_tr_b16 v[174:175], v237 offset:24576
	ds_read_b64_tr_b16 v[176:177], v237 offset:28672
	ds_read_b64_tr_b16 v[178:179], v237 offset:512
	ds_read_b64_tr_b16 v[180:181], v237 offset:4608
	ds_read_b64_tr_b16 v[182:183], v237 offset:8704
	ds_read_b64_tr_b16 v[184:185], v237 offset:12800
	ds_read_b64_tr_b16 v[186:187], v237 offset:16896
	ds_read_b64_tr_b16 v[188:189], v237 offset:20992
	ds_read_b64_tr_b16 v[190:191], v237 offset:25088
	ds_read_b64_tr_b16 v[192:193], v237 offset:29184
	s_waitcnt lgkmcnt(8)
	v_mfma_f32_32x32x16_bf16 v[0:15], v[162:165], v[196:199], v[0:15]
	v_mfma_f32_32x32x16_bf16 v[0:15], v[166:169], v[200:203], v[0:15]
	v_mfma_f32_32x32x16_bf16 v[0:15], v[170:173], v[204:207], v[0:15]
	v_mfma_f32_32x32x16_bf16 v[0:15], v[174:177], v[208:211], v[0:15]
	ds_read_b64_tr_b16 v[162:163], v237 offset:1024
	ds_read_b64_tr_b16 v[164:165], v237 offset:5120
	ds_read_b64_tr_b16 v[166:167], v237 offset:9216
	ds_read_b64_tr_b16 v[168:169], v237 offset:13312
	ds_read_b64_tr_b16 v[170:171], v237 offset:17408
	ds_read_b64_tr_b16 v[172:173], v237 offset:21504
	ds_read_b64_tr_b16 v[174:175], v237 offset:25600
	ds_read_b64_tr_b16 v[176:177], v237 offset:29696
	s_waitcnt lgkmcnt(8)
	v_mfma_f32_32x32x16_bf16 v[16:31], v[178:181], v[196:199], v[16:31]
	v_mfma_f32_32x32x16_bf16 v[16:31], v[182:185], v[200:203], v[16:31]
	v_mfma_f32_32x32x16_bf16 v[16:31], v[186:189], v[204:207], v[16:31]
	v_mfma_f32_32x32x16_bf16 v[16:31], v[190:193], v[208:211], v[16:31]
	ds_read_b64_tr_b16 v[178:179], v237 offset:1536
	ds_read_b64_tr_b16 v[180:181], v237 offset:5632
	ds_read_b64_tr_b16 v[182:183], v237 offset:9728
	ds_read_b64_tr_b16 v[184:185], v237 offset:13824
	ds_read_b64_tr_b16 v[186:187], v237 offset:17920
	ds_read_b64_tr_b16 v[188:189], v237 offset:22016
	ds_read_b64_tr_b16 v[190:191], v237 offset:26112
	ds_read_b64_tr_b16 v[192:193], v237 offset:30208
	s_waitcnt lgkmcnt(8)
	v_mfma_f32_32x32x16_bf16 v[32:47], v[162:165], v[196:199], v[32:47]
	v_mfma_f32_32x32x16_bf16 v[32:47], v[166:169], v[200:203], v[32:47]
	v_mfma_f32_32x32x16_bf16 v[32:47], v[170:173], v[204:207], v[32:47]
	v_mfma_f32_32x32x16_bf16 v[32:47], v[174:177], v[208:211], v[32:47]
	ds_read_b64_tr_b16 v[162:163], v237 offset:2048
	ds_read_b64_tr_b16 v[164:165], v237 offset:6144
	ds_read_b64_tr_b16 v[166:167], v237 offset:10240
	ds_read_b64_tr_b16 v[168:169], v237 offset:14336
	ds_read_b64_tr_b16 v[170:171], v237 offset:18432
	ds_read_b64_tr_b16 v[172:173], v237 offset:22528
	ds_read_b64_tr_b16 v[174:175], v237 offset:26624
	ds_read_b64_tr_b16 v[176:177], v237 offset:30720
	s_waitcnt lgkmcnt(8)
	v_mfma_f32_32x32x16_bf16 v[48:63], v[178:181], v[196:199], v[48:63]
	v_mfma_f32_32x32x16_bf16 v[48:63], v[182:185], v[200:203], v[48:63]
	v_mfma_f32_32x32x16_bf16 v[48:63], v[186:189], v[204:207], v[48:63]
	v_mfma_f32_32x32x16_bf16 v[48:63], v[190:193], v[208:211], v[48:63]
	ds_read_b64_tr_b16 v[178:179], v237 offset:2560
	ds_read_b64_tr_b16 v[180:181], v237 offset:6656
	ds_read_b64_tr_b16 v[182:183], v237 offset:10752
	ds_read_b64_tr_b16 v[184:185], v237 offset:14848
	ds_read_b64_tr_b16 v[186:187], v237 offset:18944
	ds_read_b64_tr_b16 v[188:189], v237 offset:23040
	ds_read_b64_tr_b16 v[190:191], v237 offset:27136
	ds_read_b64_tr_b16 v[192:193], v237 offset:31232
	s_waitcnt lgkmcnt(8)
	v_mfma_f32_32x32x16_bf16 v[64:79], v[162:165], v[196:199], v[64:79]
	v_mfma_f32_32x32x16_bf16 v[64:79], v[166:169], v[200:203], v[64:79]
	v_mfma_f32_32x32x16_bf16 v[64:79], v[170:173], v[204:207], v[64:79]
	v_mfma_f32_32x32x16_bf16 v[64:79], v[174:177], v[208:211], v[64:79]
	ds_read_b64_tr_b16 v[162:163], v237 offset:3072
	ds_read_b64_tr_b16 v[164:165], v237 offset:7168
	ds_read_b64_tr_b16 v[166:167], v237 offset:11264
	ds_read_b64_tr_b16 v[168:169], v237 offset:15360
	ds_read_b64_tr_b16 v[170:171], v237 offset:19456
	ds_read_b64_tr_b16 v[172:173], v237 offset:23552
	ds_read_b64_tr_b16 v[174:175], v237 offset:27648
	ds_read_b64_tr_b16 v[176:177], v237 offset:31744
	s_waitcnt lgkmcnt(8)
	v_mfma_f32_32x32x16_bf16 v[80:95], v[178:181], v[196:199], v[80:95]
	v_mfma_f32_32x32x16_bf16 v[80:95], v[182:185], v[200:203], v[80:95]
	v_mfma_f32_32x32x16_bf16 v[80:95], v[186:189], v[204:207], v[80:95]
	v_mfma_f32_32x32x16_bf16 v[80:95], v[190:193], v[208:211], v[80:95]
	ds_read_b64_tr_b16 v[178:179], v237 offset:3584
	ds_read_b64_tr_b16 v[180:181], v237 offset:7680
	ds_read_b64_tr_b16 v[182:183], v237 offset:11776
	ds_read_b64_tr_b16 v[184:185], v237 offset:15872
	ds_read_b64_tr_b16 v[186:187], v237 offset:19968
	ds_read_b64_tr_b16 v[188:189], v237 offset:24064
	ds_read_b64_tr_b16 v[190:191], v237 offset:28160
	ds_read_b64_tr_b16 v[192:193], v237 offset:32256
	s_waitcnt lgkmcnt(8)
	v_mfma_f32_32x32x16_bf16 v[98:113], v[162:165], v[196:199], v[98:113]
	v_mfma_f32_32x32x16_bf16 v[98:113], v[166:169], v[200:203], v[98:113]
	v_mfma_f32_32x32x16_bf16 v[98:113], v[170:173], v[204:207], v[98:113]
	v_mfma_f32_32x32x16_bf16 v[98:113], v[174:177], v[208:211], v[98:113]
	s_waitcnt lgkmcnt(0)
	v_mfma_f32_32x32x16_bf16 v[114:129], v[178:181], v[196:199], v[114:129]
	v_mfma_f32_32x32x16_bf16 v[114:129], v[182:185], v[200:203], v[114:129]
	v_mfma_f32_32x32x16_bf16 v[114:129], v[186:189], v[204:207], v[114:129]
	v_mfma_f32_32x32x16_bf16 v[114:129], v[190:193], v[208:211], v[114:129]
	s_waitcnt vmcnt(0)
	s_barrier
	s_cmp_le_u32 s13, 3
	s_cbranch_scc1 .Lam_nodma_b
	s_add_i32 m0, s39, 0xc000
	s_nop 0
	global_load_lds_dwordx4 v244, s[18:19]
	s_add_i32 m0, s39, 0xc400
	s_nop 0
	global_load_lds_dwordx4 v245, s[18:19]
	s_add_i32 m0, s47, 0xc000
	s_nop 0
	global_load_lds_dwordx4 v246, s[20:21]
	s_add_i32 m0, s47, 0xc400
	s_nop 0
	global_load_lds_dwordx4 v247, s[20:21]
	s_add_i32 m0, s47, 0xc800
	s_nop 0
	global_load_lds_dwordx4 v248, s[20:21]
	s_add_i32 m0, s47, 0xcc00
	s_nop 0
	global_load_lds_dwordx4 v249, s[20:21]
	s_add_u32 s18, s18, 0x40000
	s_addc_u32 s19, s19, 0
	s_add_u32 s20, s20, 0x40000
	s_addc_u32 s21, s21, 0
.Lam_nodma_b:
	s_sub_i32 s13, s13, 2
	s_cmp_gt_u32 s13, 0
	s_cbranch_scc1 .Lam_loop
	v_rcp_f32_e32 v240, v239
	v_and_b32_e32 v241, 31, v96
	s_lshl_b32 s37, s36, 5
	v_add_u32_e32 v241, s37, v241
	v_lshlrev_b32_e32 v241, 13, v241
	v_lshrrev_b32_e32 v242, 5, v96
	v_lshl_add_u32 v241, v242, 4, v241
	v_mul_f32_e32 v212, v0, v240
	v_mul_f32_e32 v213, v1, v240
	v_mul_f32_e32 v214, v2, v240
	v_mul_f32_e32 v215, v3, v240
	v_mul_f32_e32 v216, v4, v240
	v_mul_f32_e32 v217, v5, v240
	v_mul_f32_e32 v218, v6, v240
	v_mul_f32_e32 v219, v7, v240
	v_cvt_pk_bf16_f32 v162, v212, v213
	v_cvt_pk_bf16_f32 v163, v214, v215
	v_cvt_pk_bf16_f32 v164, v216, v217
	v_cvt_pk_bf16_f32 v165, v218, v219
	s_nop 1
	v_permlane32_swap_b32_e32 v162, v164
	v_permlane32_swap_b32_e32 v163, v165
	global_store_dwordx4 v241, v[162:165], s[22:23]
	v_mul_f32_e32 v220, v8, v240
	v_mul_f32_e32 v221, v9, v240
	v_mul_f32_e32 v222, v10, v240
	v_mul_f32_e32 v223, v11, v240
	v_mul_f32_e32 v224, v12, v240
	v_mul_f32_e32 v225, v13, v240
	v_mul_f32_e32 v226, v14, v240
	v_mul_f32_e32 v227, v15, v240
	v_cvt_pk_bf16_f32 v166, v220, v221
	v_cvt_pk_bf16_f32 v167, v222, v223
	v_cvt_pk_bf16_f32 v168, v224, v225
	v_cvt_pk_bf16_f32 v169, v226, v227
	s_nop 1
	v_permlane32_swap_b32_e32 v166, v168
	v_permlane32_swap_b32_e32 v167, v169
	global_store_dwordx4 v241, v[166:169], s[22:23] offset:32
	v_mul_f32_e32 v212, v16, v240
	v_mul_f32_e32 v213, v17, v240
	v_mul_f32_e32 v214, v18, v240
	v_mul_f32_e32 v215, v19, v240
	v_mul_f32_e32 v216, v20, v240
	v_mul_f32_e32 v217, v21, v240
	v_mul_f32_e32 v218, v22, v240
	v_mul_f32_e32 v219, v23, v240
	v_cvt_pk_bf16_f32 v170, v212, v213
	v_cvt_pk_bf16_f32 v171, v214, v215
	v_cvt_pk_bf16_f32 v172, v216, v217
	v_cvt_pk_bf16_f32 v173, v218, v219
	s_nop 1
	v_permlane32_swap_b32_e32 v170, v172
	v_permlane32_swap_b32_e32 v171, v173
	global_store_dwordx4 v241, v[170:173], s[22:23] offset:64
	v_mul_f32_e32 v220, v24, v240
	v_mul_f32_e32 v221, v25, v240
	v_mul_f32_e32 v222, v26, v240
	v_mul_f32_e32 v223, v27, v240
	v_mul_f32_e32 v224, v28, v240
	v_mul_f32_e32 v225, v29, v240
	v_mul_f32_e32 v226, v30, v240
	v_mul_f32_e32 v227, v31, v240
	v_cvt_pk_bf16_f32 v174, v220, v221
	v_cvt_pk_bf16_f32 v175, v222, v223
	v_cvt_pk_bf16_f32 v176, v224, v225
	v_cvt_pk_bf16_f32 v177, v226, v227
	s_nop 1
	v_permlane32_swap_b32_e32 v174, v176
	v_permlane32_swap_b32_e32 v175, v177
	global_store_dwordx4 v241, v[174:177], s[22:23] offset:96
	v_mul_f32_e32 v212, v32, v240
	v_mul_f32_e32 v213, v33, v240
	v_mul_f32_e32 v214, v34, v240
	v_mul_f32_e32 v215, v35, v240
	v_mul_f32_e32 v216, v36, v240
	v_mul_f32_e32 v217, v37, v240
	v_mul_f32_e32 v218, v38, v240
	v_mul_f32_e32 v219, v39, v240
	v_cvt_pk_bf16_f32 v178, v212, v213
	v_cvt_pk_bf16_f32 v179, v214, v215
	v_cvt_pk_bf16_f32 v180, v216, v217
	v_cvt_pk_bf16_f32 v181, v218, v219
	s_nop 1
	v_permlane32_swap_b32_e32 v178, v180
	v_permlane32_swap_b32_e32 v179, v181
	global_store_dwordx4 v241, v[178:181], s[22:23] offset:128
	v_mul_f32_e32 v220, v40, v240
	v_mul_f32_e32 v221, v41, v240
	v_mul_f32_e32 v222, v42, v240
	v_mul_f32_e32 v223, v43, v240
	v_mul_f32_e32 v224, v44, v240
	v_mul_f32_e32 v225, v45, v240
	v_mul_f32_e32 v226, v46, v240
	v_mul_f32_e32 v227, v47, v240
	v_cvt_pk_bf16_f32 v182, v220, v221
	v_cvt_pk_bf16_f32 v183, v222, v223
	v_cvt_pk_bf16_f32 v184, v224, v225
	v_cvt_pk_bf16_f32 v185, v226, v227
	s_nop 1
	v_permlane32_swap_b32_e32 v182, v184
	v_permlane32_swap_b32_e32 v183, v185
	global_store_dwordx4 v241, v[182:185], s[22:23] offset:160
	v_mul_f32_e32 v212, v48, v240
	v_mul_f32_e32 v213, v49, v240
	v_mul_f32_e32 v214, v50, v240
	v_mul_f32_e32 v215, v51, v240
	v_mul_f32_e32 v216, v52, v240
	v_mul_f32_e32 v217, v53, v240
	v_mul_f32_e32 v218, v54, v240
	v_mul_f32_e32 v219, v55, v240
	v_cvt_pk_bf16_f32 v186, v212, v213
	v_cvt_pk_bf16_f32 v187, v214, v215
	v_cvt_pk_bf16_f32 v188, v216, v217
	v_cvt_pk_bf16_f32 v189, v218, v219
	s_nop 1
	v_permlane32_swap_b32_e32 v186, v188
	v_permlane32_swap_b32_e32 v187, v189
	global_store_dwordx4 v241, v[186:189], s[22:23] offset:192
	v_mul_f32_e32 v220, v56, v240
	v_mul_f32_e32 v221, v57, v240
	v_mul_f32_e32 v222, v58, v240
	v_mul_f32_e32 v223, v59, v240
	v_mul_f32_e32 v224, v60, v240
	v_mul_f32_e32 v225, v61, v240
	v_mul_f32_e32 v226, v62, v240
	v_mul_f32_e32 v227, v63, v240
	v_cvt_pk_bf16_f32 v190, v220, v221
	v_cvt_pk_bf16_f32 v191, v222, v223
	v_cvt_pk_bf16_f32 v192, v224, v225
	v_cvt_pk_bf16_f32 v193, v226, v227
	s_nop 1
	v_permlane32_swap_b32_e32 v190, v192
	v_permlane32_swap_b32_e32 v191, v193
	global_store_dwordx4 v241, v[190:193], s[22:23] offset:224
	v_mul_f32_e32 v212, v64, v240
	v_mul_f32_e32 v213, v65, v240
	v_mul_f32_e32 v214, v66, v240
	v_mul_f32_e32 v215, v67, v240
	v_mul_f32_e32 v216, v68, v240
	v_mul_f32_e32 v217, v69, v240
	v_mul_f32_e32 v218, v70, v240
	v_mul_f32_e32 v219, v71, v240
	v_cvt_pk_bf16_f32 v162, v212, v213
	v_cvt_pk_bf16_f32 v163, v214, v215
	v_cvt_pk_bf16_f32 v164, v216, v217
	v_cvt_pk_bf16_f32 v165, v218, v219
	s_nop 1
	v_permlane32_swap_b32_e32 v162, v164
	v_permlane32_swap_b32_e32 v163, v165
	global_store_dwordx4 v241, v[162:165], s[22:23] offset:256
	v_mul_f32_e32 v220, v72, v240
	v_mul_f32_e32 v221, v73, v240
	v_mul_f32_e32 v222, v74, v240
	v_mul_f32_e32 v223, v75, v240
	v_mul_f32_e32 v224, v76, v240
	v_mul_f32_e32 v225, v77, v240
	v_mul_f32_e32 v226, v78, v240
	v_mul_f32_e32 v227, v79, v240
	v_cvt_pk_bf16_f32 v166, v220, v221
	v_cvt_pk_bf16_f32 v167, v222, v223
	v_cvt_pk_bf16_f32 v168, v224, v225
	v_cvt_pk_bf16_f32 v169, v226, v227
	s_nop 1
	v_permlane32_swap_b32_e32 v166, v168
	v_permlane32_swap_b32_e32 v167, v169
	global_store_dwordx4 v241, v[166:169], s[22:23] offset:288
	v_mul_f32_e32 v212, v80, v240
	v_mul_f32_e32 v213, v81, v240
	v_mul_f32_e32 v214, v82, v240
	v_mul_f32_e32 v215, v83, v240
	v_mul_f32_e32 v216, v84, v240
	v_mul_f32_e32 v217, v85, v240
	v_mul_f32_e32 v218, v86, v240
	v_mul_f32_e32 v219, v87, v240
	v_cvt_pk_bf16_f32 v170, v212, v213
	v_cvt_pk_bf16_f32 v171, v214, v215
	v_cvt_pk_bf16_f32 v172, v216, v217
	v_cvt_pk_bf16_f32 v173, v218, v219
	s_nop 1
	v_permlane32_swap_b32_e32 v170, v172
	v_permlane32_swap_b32_e32 v171, v173
	global_store_dwordx4 v241, v[170:173], s[22:23] offset:320
	v_mul_f32_e32 v220, v88, v240
	v_mul_f32_e32 v221, v89, v240
	v_mul_f32_e32 v222, v90, v240
	v_mul_f32_e32 v223, v91, v240
	v_mul_f32_e32 v224, v92, v240
	v_mul_f32_e32 v225, v93, v240
	v_mul_f32_e32 v226, v94, v240
	v_mul_f32_e32 v227, v95, v240
	v_cvt_pk_bf16_f32 v174, v220, v221
	v_cvt_pk_bf16_f32 v175, v222, v223
	v_cvt_pk_bf16_f32 v176, v224, v225
	v_cvt_pk_bf16_f32 v177, v226, v227
	s_nop 1
	v_permlane32_swap_b32_e32 v174, v176
	v_permlane32_swap_b32_e32 v175, v177
	global_store_dwordx4 v241, v[174:177], s[22:23] offset:352
	v_mul_f32_e32 v212, v98, v240
	v_mul_f32_e32 v213, v99, v240
	v_mul_f32_e32 v214, v100, v240
	v_mul_f32_e32 v215, v101, v240
	v_mul_f32_e32 v216, v102, v240
	v_mul_f32_e32 v217, v103, v240
	v_mul_f32_e32 v218, v104, v240
	v_mul_f32_e32 v219, v105, v240
	v_cvt_pk_bf16_f32 v178, v212, v213
	v_cvt_pk_bf16_f32 v179, v214, v215
	v_cvt_pk_bf16_f32 v180, v216, v217
	v_cvt_pk_bf16_f32 v181, v218, v219
	s_nop 1
	v_permlane32_swap_b32_e32 v178, v180
	v_permlane32_swap_b32_e32 v179, v181
	global_store_dwordx4 v241, v[178:181], s[22:23] offset:384
	v_mul_f32_e32 v220, v106, v240
	v_mul_f32_e32 v221, v107, v240
	v_mul_f32_e32 v222, v108, v240
	v_mul_f32_e32 v223, v109, v240
	v_mul_f32_e32 v224, v110, v240
	v_mul_f32_e32 v225, v111, v240
	v_mul_f32_e32 v226, v112, v240
	v_mul_f32_e32 v227, v113, v240
	v_cvt_pk_bf16_f32 v182, v220, v221
	v_cvt_pk_bf16_f32 v183, v222, v223
	v_cvt_pk_bf16_f32 v184, v224, v225
	v_cvt_pk_bf16_f32 v185, v226, v227
	s_nop 1
	v_permlane32_swap_b32_e32 v182, v184
	v_permlane32_swap_b32_e32 v183, v185
	global_store_dwordx4 v241, v[182:185], s[22:23] offset:416
	v_mul_f32_e32 v212, v114, v240
	v_mul_f32_e32 v213, v115, v240
	v_mul_f32_e32 v214, v116, v240
	v_mul_f32_e32 v215, v117, v240
	v_mul_f32_e32 v216, v118, v240
	v_mul_f32_e32 v217, v119, v240
	v_mul_f32_e32 v218, v120, v240
	v_mul_f32_e32 v219, v121, v240
	v_cvt_pk_bf16_f32 v186, v212, v213
	v_cvt_pk_bf16_f32 v187, v214, v215
	v_cvt_pk_bf16_f32 v188, v216, v217
	v_cvt_pk_bf16_f32 v189, v218, v219
	s_nop 1
	v_permlane32_swap_b32_e32 v186, v188
	v_permlane32_swap_b32_e32 v187, v189
	global_store_dwordx4 v241, v[186:189], s[22:23] offset:448
	v_mul_f32_e32 v220, v122, v240
	v_mul_f32_e32 v221, v123, v240
	v_mul_f32_e32 v222, v124, v240
	v_mul_f32_e32 v223, v125, v240
	v_mul_f32_e32 v224, v126, v240
	v_mul_f32_e32 v225, v127, v240
	v_mul_f32_e32 v226, v128, v240
	v_mul_f32_e32 v227, v129, v240
	v_cvt_pk_bf16_f32 v190, v220, v221
	v_cvt_pk_bf16_f32 v191, v222, v223
	v_cvt_pk_bf16_f32 v192, v224, v225
	v_cvt_pk_bf16_f32 v193, v226, v227
	s_nop 1
	v_permlane32_swap_b32_e32 v190, v192
	v_permlane32_swap_b32_e32 v191, v193
	global_store_dwordx4 v241, v[190:193], s[22:23] offset:480
	s_waitcnt lgkmcnt(0)
	s_barrier
	s_brev_b32 s30, 64
	v_readlane_b32 s31, v254, 63
	s_movk_i32 s61, 0x1000
	s_mov_b64 s[6:7], 0
